# ret_out cross term: per-step Q fragments prefetched 4 steps ahead by LDS-DMA into the idle P-tile region (ds_read_b128 at use), slice loads get their own counted wait
# speedup vs baseline: 1.0051x; 1.0001x over previous
; __device__ __forceinline__ float head_log2_gamma(int h) { return __builtin_log2f(1.0f - __builtin_exp2f(-5.0f - (float)h)); }
; #define R2_LOADS(src, rstride, sl) do { _Pragma("unroll") for (int i = 0; i < 4; ++i) sr[i] = *(const v4u*)((src) + (size_t)(srow + 128 * i) * (rstride) + 32 * (sl) + 8 * sc4); } while (0)
; #define R2_STORES(bf) do { _Pragma("unroll") for (int i = 0; i < 4; ++i) *(LAS v4u*)(lds + (bf) * R2_SBUF + sso + 128 * i * 64) = sr[i]; } while (0)
;     ...
;     for (int task = bid; task < 512; task += gridDim.x) {
;         const int bh = task >> 6, c = (task & 63) ^ (task >> 8), h = bh & 3, odd = c & 1, tk0 = (c & ~1) * 128, tq0 = c * 128;
;         const float lg2 = head_log2_gamma(h);
;         f32x16 acc[8];
; #pragma unroll
;         for (int et = 0; et < 8; ++et)
; #pragma unroll
;             for (int i = 0; i < 16; ++i) acc[et][i] = 0.f;
;         v4u sr[4];
;     ...
;         if (!(dry && (R2_SKIP & 1))) { R2_IDS const bf16* qg = R2_QG; const bf16* src = ST + (((size_t)(bh * 32 + (c >> 1))) * 512) * 256;
;           __syncthreads();
;           R2_LOADS(src, 256, 0); R2_STORES(0);
;           __syncthreads();
;           for (int sl = 0; sl < 8; ++sl) {
;               if (sl + 1 < 8) R2_LOADS(src, 256, sl + 1);
;               const bf16x8_t bq0 = *(const bf16x8_t*)(qg + 32 * sl), bq1 = *(const bf16x8_t*)(qg + 32 * sl + 16);
;               R2_SLICE(sl & 1, bq0, bq1);
;               if (sl + 1 < 8) R2_STORES((sl + 1) & 1);
;               __syncthreads();
;           } }
.LBB0_718:
	s_ashr_i32 s7, s36, 6
	s_and_b32 s4, s36, 63
	s_ashr_i32 s5, s36, 8
	s_xor_b32 s40, s4, s5
	s_and_b32 s4, s7, 3
	s_waitcnt vmcnt(0)
	v_cvt_f32_ubyte0_e32 v0, s4
	v_sub_f32_e32 v0, 0xc0a00000, v0
	s_mov_b32 s6, 0xc2fc0000
	v_cmp_gt_f32_e32 vcc, s6, v0
	s_lshl_b32 s5, s40, 7
	s_and_b64 s[34:35], vcc, exec
	v_cndmask_b32_e32 v1, 0, v235, vcc
	v_add_f32_e32 v0, v0, v1
	v_exp_f32_e32 v0, v0
	s_cselect_b32 s6, 0xffffffc0, 0
	v_mov_b32_e32 v20, v33
	s_lshl_b32 s34, s7, 5
	v_ldexp_f32 v0, v0, s6
	s_ashr_i32 s35, s40, 1
	v_sub_f32_e32 v140, 1.0, v0
	s_lshl_b32 s41, s7, 13
	v_and_b32_e32 v0, 31, v20
	s_add_i32 s34, s35, s34
	v_or_b32_e32 v24, s30, v0
	s_add_i32 s19, s5, s41
	v_or_b32_e32 v0, s47, v0
	s_ashr_i32 s35, s34, 31
	s_and_b32 s6, s5, 0xffffff00
	v_or_b32_e32 v0, s19, v0
	s_lshl_b64 s[34:35], s[34:35], 18
	v_ashrrev_i32_e32 v16, 2, v20
	v_lshlrev_b32_e32 v2, 4, v20
	v_ashrrev_i32_e32 v1, 31, v0
	s_add_u32 s34, s43, s34
	v_lshlrev_b64 v[18:19], 9, v[0:1]
	s_addc_u32 s35, s44, s35
	v_and_b32_e32 v0, 48, v2
	v_mov_b32_e32 v1, v32
	v_ashrrev_i32_e32 v17, 31, v16
	v_bitop3_b32 v23, v2, 48, v20 bitop3:0x48
	v_lshl_add_u64 v[0:1], s[34:35], 0, v[0:1]
	v_lshlrev_b64 v[2:3], 9, v[16:17]
	v_lshl_add_u64 v[130:131], v[0:1], 0, v[2:3]
	s_mov_b64 s[34:35], 0x10000
	v_lshl_add_u64 v[132:133], v[130:131], 0, s[34:35]
	s_mov_b32 s34, 0x10000
	v_add_co_u32_e32 v4, vcc, s34, v130
	s_mov_b32 s34, 0x20000
	s_nop 0
	v_addc_co_u32_e32 v5, vcc, 0, v131, vcc
	v_add_co_u32_e32 v8, vcc, s34, v130
	s_mov_b64 s[34:35], 0x30000
	s_barrier
	global_load_dwordx4 v[0:3], v[130:131], off
	v_addc_co_u32_e32 v9, vcc, 0, v131, vcc
	v_lshl_add_u64 v[136:137], v[130:131], 0, s[34:35]
	s_mov_b32 s34, 0x30000
	global_load_dwordx4 v[4:7], v[4:5], off
	v_add_co_u32_e32 v12, vcc, s34, v130
	global_load_dwordx4 v[8:11], v[8:9], off
	s_nop 0
	v_addc_co_u32_e32 v13, vcc, 0, v131, vcc
	global_load_dwordx4 v[12:15], v[12:13], off
	v_lshl_add_u32 v16, v16, 6, 0
	s_mov_b32 s34, 0x10800
	v_bfe_u32 v22, v20, 5, 1
	v_add3_u32 v141, v16, v23, s34
	v_lshl_add_u64 v[18:19], s[24:25], 0, v[18:19]
	v_lshl_add_u64 v[134:135], v[130:131], 0, s[12:13]
	v_lshrrev_b32_e32 v21, 5, v20
	v_bfe_u32 v17, v20, 2, 2
	v_lshl_add_u32 v147, v24, 6, 0
	s_and_b32 s40, s40, 1
	s_waitcnt vmcnt(3)
	ds_write_b128 v141, v[0:3]
	s_waitcnt vmcnt(2)
	ds_write_b128 v141, v[4:7] offset:8192
	s_waitcnt vmcnt(1)
	ds_write_b128 v141, v[8:11] offset:16384
	s_waitcnt vmcnt(0)
	ds_write_b128 v141, v[12:15] offset:24576
	v_lshlrev_b32_e32 v0, 4, v22
	v_mov_b32_e32 v1, v32
	v_lshl_add_u64 v[138:139], v[18:19], 0, v[0:1]
	v_readfirstlane_b32 s70, v228
	s_nop 3
	s_lshr_b32 s70, s70, 6
	s_lshl_b32 s70, s70, 13
	s_add_i32 s70, s70, 0x400
	s_add_i32 m0, s70, 0x0
	s_nop 0
	global_load_lds_dwordx4 v[138:139], off
	s_add_i32 m0, s70, 0x3e0
	s_nop 0
	global_load_lds_dwordx4 v[138:139], off offset:32
	s_add_i32 m0, s70, 0x7c0
	s_nop 0
	global_load_lds_dwordx4 v[138:139], off offset:64
	s_add_i32 m0, s70, 0xba0
	s_nop 0
	global_load_lds_dwordx4 v[138:139], off offset:96
	s_add_i32 m0, s70, 0xf80
	s_nop 0
	global_load_lds_dwordx4 v[138:139], off offset:128
	s_add_i32 m0, s70, 0x1360
	s_nop 0
	global_load_lds_dwordx4 v[138:139], off offset:160
	s_add_i32 m0, s70, 0x1740
	s_nop 0
	global_load_lds_dwordx4 v[138:139], off offset:192
	s_add_i32 m0, s70, 0x1b20
	s_nop 0
	global_load_lds_dwordx4 v[138:139], off offset:224
	s_waitcnt lgkmcnt(0)
	s_barrier
	global_load_dwordx4 v[148:151], v[130:131], off offset:64
	global_load_dwordx4 v[152:155], v[132:133], off offset:64
	global_load_dwordx4 v[156:159], v[134:135], off offset:64
	global_load_dwordx4 v[160:163], v[136:137], off offset:64
	s_waitcnt vmcnt(10)
	v_and_b32_e32 v50, 63, v228
	v_lshl_add_u32 v50, v50, 4, s70
	ds_read_b128 v[50:53], v50
	v_and_b32_e32 v164, 63, v228
	v_lshl_add_u32 v164, v164, 4, s70
	ds_read_b128 v[164:167], v164 offset:1024
	v_bitop3_b32 v0, v21, v17, 1 bitop3:0x6c
	v_lshlrev_b32_e32 v192, 4, v0
	v_bitop3_b32 v0, v22, v17, 2 bitop3:0x36
	v_lshlrev_b32_e32 v193, 4, v0
	v_add_u32_e32 v4, 0x10800, v147
	v_add_u32_e32 v142, v4, v192
	v_add_u32_e32 v143, v4, v193
	ds_read_b128 v[0:3], v142
	ds_read_b128 v[16:19], v143
	v_add_u32_e32 v4, 0x11000, v147
	v_add_u32_e32 v144, v4, v192
	v_add_u32_e32 v145, v4, v193
	ds_read_b128 v[20:23], v144
	ds_read_b128 v[34:37], v145
	v_add_u32_e32 v4, 0x11800, v147
	v_add_u32_e32 v146, v4, v192
	v_add_u32_e32 v195, v4, v193
	ds_read_b128 v[38:41], v146
	ds_read_b128 v[54:57], v195
	s_waitcnt lgkmcnt(5)
	v_mfma_f32_32x32x16_bf16 v[0:15], v[0:3], v[50:53], 0
	s_waitcnt lgkmcnt(4)
	v_mfma_f32_32x32x16_bf16 v[0:15], v[16:19], v[164:167], v[0:15]
	s_add_i32 m0, s70, 0xffffff00
	s_nop 0
	global_load_lds_dwordx4 v[138:139], off offset:256
	s_add_i32 m0, s70, 0x2e0
	s_nop 0
	global_load_lds_dwordx4 v[138:139], off offset:288
	v_add_u32_e32 v16, 0x12000, v147
	v_add_u32_e32 v208, v16, v192
	v_add_u32_e32 v209, v16, v193
	ds_read_b128 v[58:61], v208
	ds_read_b128 v[62:65], v209
	s_waitcnt lgkmcnt(5)
	v_mfma_f32_32x32x16_bf16 v[16:31], v[20:23], v[50:53], 0
	s_waitcnt lgkmcnt(4)
	v_mfma_f32_32x32x16_bf16 v[16:31], v[34:37], v[164:167], v[16:31]
	v_add_u32_e32 v34, 0x12800, v147
	v_add_u32_e32 v210, v34, v192
	v_add_u32_e32 v211, v34, v193
	ds_read_b128 v[82:85], v210
	ds_read_b128 v[86:89], v211
	s_waitcnt lgkmcnt(5)
	v_mfma_f32_32x32x16_bf16 v[34:49], v[38:41], v[50:53], 0
	s_waitcnt lgkmcnt(4)
	v_mfma_f32_32x32x16_bf16 v[34:49], v[54:57], v[164:167], v[34:49]
	v_add_u32_e32 v54, 0x13000, v147
	v_add_u32_e32 v212, v54, v192
	v_add_u32_e32 v213, v54, v193
	ds_read_b128 v[54:57], v212
	ds_read_b128 v[90:93], v213
	s_waitcnt lgkmcnt(5)
	v_mfma_f32_32x32x16_bf16 v[66:81], v[58:61], v[50:53], 0
	s_waitcnt lgkmcnt(4)
	v_mfma_f32_32x32x16_bf16 v[66:81], v[62:65], v[164:167], v[66:81]
	v_add_u32_e32 v58, 0x13800, v147
	v_add_u32_e32 v214, v58, v192
	v_add_u32_e32 v215, v58, v193
	ds_read_b128 v[58:61], v214
	ds_read_b128 v[62:65], v215
	s_waitcnt lgkmcnt(5)
	v_mfma_f32_32x32x16_bf16 v[98:113], v[82:85], v[50:53], 0
	s_waitcnt lgkmcnt(4)
	v_mfma_f32_32x32x16_bf16 v[98:113], v[86:89], v[164:167], v[98:113]
	v_add_u32_e32 v82, 0x14000, v147
	v_add_u32_e32 v216, v82, v192
	v_add_u32_e32 v217, v82, v193
	ds_read_b128 v[168:171], v216
	ds_read_b128 v[172:175], v217
	s_waitcnt lgkmcnt(5)
	v_mfma_f32_32x32x16_bf16 v[114:129], v[54:57], v[50:53], 0
	s_waitcnt lgkmcnt(4)
	v_mfma_f32_32x32x16_bf16 v[114:129], v[90:93], v[164:167], v[114:129]
	s_waitcnt lgkmcnt(3)
	v_mfma_f32_32x32x16_bf16 v[82:97], v[58:61], v[50:53], 0
	s_waitcnt lgkmcnt(2)
	v_mfma_f32_32x32x16_bf16 v[82:97], v[62:65], v[164:167], v[82:97]
	s_waitcnt lgkmcnt(1)
	v_mfma_f32_32x32x16_bf16 v[50:65], v[168:171], v[50:53], 0
	s_waitcnt lgkmcnt(0)
	v_mfma_f32_32x32x16_bf16 v[50:65], v[172:175], v[164:167], v[50:65]
	s_waitcnt vmcnt(2)
	ds_write_b128 v141, v[148:151] offset:32768
	ds_write_b128 v141, v[152:155] offset:40960
	ds_write_b128 v141, v[156:159] offset:49152
	ds_write_b128 v141, v[160:163] offset:57344
	s_waitcnt lgkmcnt(0)
	s_barrier
; #define R2_LOADS(src, rstride, sl) do { _Pragma("unroll") for (int i = 0; i < 4; ++i) sr[i] = *(const v4u*)((src) + (size_t)(srow + 128 * i) * (rstride) + 32 * (sl) + 8 * sc4); } while (0)
; #define R2_STORES(bf) do { _Pragma("unroll") for (int i = 0; i < 4; ++i) *(LAS v4u*)(lds + (bf) * R2_SBUF + sso + 128 * i * 64) = sr[i]; } while (0)
;     ...
;           for (int sl = 0; sl < 8; ++sl) {
;               if (sl + 1 < 8) R2_LOADS(src, 256, sl + 1);
;               const bf16x8_t bq0 = *(const bf16x8_t*)(qg + 32 * sl), bq1 = *(const bf16x8_t*)(qg + 32 * sl + 16);
;               R2_SLICE(sl & 1, bq0, bq1);
;               if (sl + 1 < 8) R2_STORES((sl + 1) & 1);
;               __syncthreads();
;           } }
	global_load_dwordx4 v[148:151], v[130:131], off offset:128
	global_load_dwordx4 v[152:155], v[132:133], off offset:128
	global_load_dwordx4 v[156:159], v[134:135], off offset:128
	global_load_dwordx4 v[160:163], v[136:137], off offset:128
	s_waitcnt vmcnt(14)
	v_and_b32_e32 v164, 63, v228
	v_lshl_add_u32 v164, v164, 4, s70
	ds_read_b128 v[164:167], v164 offset:2048
	v_and_b32_e32 v168, 63, v228
	v_lshl_add_u32 v168, v168, 4, s70
	ds_read_b128 v[168:171], v168 offset:3072
	v_add_u32_e32 v172, 0x18800, v147
	v_add_u32_e32 v218, v172, v192
	v_add_u32_e32 v219, v172, v193
	ds_read_b128 v[172:175], v218
	ds_read_b128 v[176:179], v219
	v_add_u32_e32 v180, 0x19000, v147
	v_add_u32_e32 v220, v180, v192
	v_add_u32_e32 v221, v180, v193
	ds_read_b128 v[180:183], v220
	ds_read_b128 v[184:187], v221
	v_add_u32_e32 v188, 0x19800, v147
	v_add_u32_e32 v222, v188, v192
	v_add_u32_e32 v223, v188, v193
	ds_read_b128 v[188:191], v222
	ds_read_b128 v[204:207], v223
	s_waitcnt lgkmcnt(5)
	v_mfma_f32_32x32x16_bf16 v[0:15], v[172:175], v[164:167], v[0:15]
	s_waitcnt lgkmcnt(4)
	v_mfma_f32_32x32x16_bf16 v[0:15], v[176:179], v[168:171], v[0:15]
	s_add_i32 m0, s70, 0x6c0
	s_nop 0
	global_load_lds_dwordx4 v[138:139], off offset:320
	s_add_i32 m0, s70, 0xaa0
	s_nop 0
	global_load_lds_dwordx4 v[138:139], off offset:352
	v_add_u32_e32 v172, 0x1a000, v147
	v_add_u32_e32 v224, v172, v192
	v_add_u32_e32 v225, v172, v193
	ds_read_b128 v[172:175], v224
	ds_read_b128 v[176:179], v225
	s_waitcnt lgkmcnt(5)
	v_mfma_f32_32x32x16_bf16 v[16:31], v[180:183], v[164:167], v[16:31]
	s_waitcnt lgkmcnt(4)
	v_mfma_f32_32x32x16_bf16 v[16:31], v[184:187], v[168:171], v[16:31]
	v_add_u32_e32 v180, 0x1a800, v147
	v_add_u32_e32 v226, v180, v192
	v_add_u32_e32 v227, v180, v193
	ds_read_b128 v[180:183], v226
	ds_read_b128 v[184:187], v227
	s_waitcnt lgkmcnt(5)
	v_mfma_f32_32x32x16_bf16 v[34:49], v[188:191], v[164:167], v[34:49]
	s_waitcnt lgkmcnt(4)
	v_mfma_f32_32x32x16_bf16 v[34:49], v[204:207], v[168:171], v[34:49]
	v_add_u32_e32 v188, 0x1b000, v147
	v_add_u32_e32 v237, v188, v192
	v_add_u32_e32 v238, v188, v193
	ds_read_b128 v[188:191], v237
	ds_read_b128 v[204:207], v238
	s_waitcnt lgkmcnt(5)
	v_mfma_f32_32x32x16_bf16 v[66:81], v[172:175], v[164:167], v[66:81]
	s_waitcnt lgkmcnt(4)
	v_mfma_f32_32x32x16_bf16 v[66:81], v[176:179], v[168:171], v[66:81]
	v_add_u32_e32 v172, 0x1b800, v147
	v_add_u32_e32 v239, v172, v192
	v_add_u32_e32 v240, v172, v193
	ds_read_b128 v[172:175], v239
	ds_read_b128 v[176:179], v240
	s_waitcnt lgkmcnt(5)
	v_mfma_f32_32x32x16_bf16 v[98:113], v[180:183], v[164:167], v[98:113]
	s_waitcnt lgkmcnt(4)
	v_mfma_f32_32x32x16_bf16 v[98:113], v[184:187], v[168:171], v[98:113]
	v_add_u32_e32 v147, 0x1c000, v147
	v_add_u32_e32 v192, v147, v192
	v_add_u32_e32 v193, v147, v193
	ds_read_b128 v[180:183], v192
	ds_read_b128 v[184:187], v193
	s_waitcnt lgkmcnt(5)
	v_mfma_f32_32x32x16_bf16 v[114:129], v[188:191], v[164:167], v[114:129]
	s_waitcnt lgkmcnt(4)
	v_mfma_f32_32x32x16_bf16 v[114:129], v[204:207], v[168:171], v[114:129]
	s_waitcnt lgkmcnt(3)
	v_mfma_f32_32x32x16_bf16 v[82:97], v[172:175], v[164:167], v[82:97]
	s_waitcnt lgkmcnt(2)
	v_mfma_f32_32x32x16_bf16 v[82:97], v[176:179], v[168:171], v[82:97]
	s_waitcnt lgkmcnt(1)
	v_mfma_f32_32x32x16_bf16 v[50:65], v[180:183], v[164:167], v[50:65]
	s_waitcnt lgkmcnt(0)
	v_mfma_f32_32x32x16_bf16 v[50:65], v[184:187], v[168:171], v[50:65]
	s_waitcnt vmcnt(2)
	ds_write_b128 v141, v[148:151]
	ds_write_b128 v141, v[152:155] offset:8192
	ds_write_b128 v141, v[156:159] offset:16384
	ds_write_b128 v141, v[160:163] offset:24576
	s_waitcnt lgkmcnt(0)
	s_barrier
	global_load_dwordx4 v[148:151], v[130:131], off offset:192
	global_load_dwordx4 v[152:155], v[132:133], off offset:192
	global_load_dwordx4 v[156:159], v[134:135], off offset:192
	global_load_dwordx4 v[160:163], v[136:137], off offset:192
	s_waitcnt vmcnt(18)
	v_and_b32_e32 v164, 63, v228
	v_lshl_add_u32 v164, v164, 4, s70
	ds_read_b128 v[164:167], v164 offset:4096
	v_and_b32_e32 v168, 63, v228
	v_lshl_add_u32 v168, v168, 4, s70
	ds_read_b128 v[168:171], v168 offset:5120
	ds_read_b128 v[172:175], v142
	ds_read_b128 v[176:179], v143
	ds_read_b128 v[180:183], v144
	ds_read_b128 v[184:187], v145
	ds_read_b128 v[188:191], v146
	ds_read_b128 v[204:207], v195
	s_waitcnt lgkmcnt(5)
	v_mfma_f32_32x32x16_bf16 v[0:15], v[172:175], v[164:167], v[0:15]
	s_waitcnt lgkmcnt(4)
	v_mfma_f32_32x32x16_bf16 v[0:15], v[176:179], v[168:171], v[0:15]
	s_add_i32 m0, s70, 0xe80
	s_nop 0
	global_load_lds_dwordx4 v[138:139], off offset:384
	s_add_i32 m0, s70, 0x1260
	s_nop 0
	global_load_lds_dwordx4 v[138:139], off offset:416
	ds_read_b128 v[172:175], v208
	ds_read_b128 v[176:179], v209
	s_waitcnt lgkmcnt(5)
	v_mfma_f32_32x32x16_bf16 v[16:31], v[180:183], v[164:167], v[16:31]
	s_waitcnt lgkmcnt(4)
	v_mfma_f32_32x32x16_bf16 v[16:31], v[184:187], v[168:171], v[16:31]
	ds_read_b128 v[180:183], v210
	ds_read_b128 v[184:187], v211
	s_waitcnt lgkmcnt(5)
	v_mfma_f32_32x32x16_bf16 v[34:49], v[188:191], v[164:167], v[34:49]
	s_waitcnt lgkmcnt(4)
	v_mfma_f32_32x32x16_bf16 v[34:49], v[204:207], v[168:171], v[34:49]
	ds_read_b128 v[188:191], v212
	ds_read_b128 v[204:207], v213
	s_waitcnt lgkmcnt(5)
	v_mfma_f32_32x32x16_bf16 v[66:81], v[172:175], v[164:167], v[66:81]
	s_waitcnt lgkmcnt(4)
	v_mfma_f32_32x32x16_bf16 v[66:81], v[176:179], v[168:171], v[66:81]
	ds_read_b128 v[172:175], v214
	ds_read_b128 v[176:179], v215
	s_waitcnt lgkmcnt(5)
	v_mfma_f32_32x32x16_bf16 v[98:113], v[180:183], v[164:167], v[98:113]
	s_waitcnt lgkmcnt(4)
	v_mfma_f32_32x32x16_bf16 v[98:113], v[184:187], v[168:171], v[98:113]
	ds_read_b128 v[180:183], v216
	ds_read_b128 v[184:187], v217
	s_waitcnt lgkmcnt(5)
	v_mfma_f32_32x32x16_bf16 v[114:129], v[188:191], v[164:167], v[114:129]
	s_waitcnt lgkmcnt(4)
	v_mfma_f32_32x32x16_bf16 v[114:129], v[204:207], v[168:171], v[114:129]
	s_waitcnt lgkmcnt(3)
	v_mfma_f32_32x32x16_bf16 v[82:97], v[172:175], v[164:167], v[82:97]
	s_waitcnt lgkmcnt(2)
	v_mfma_f32_32x32x16_bf16 v[82:97], v[176:179], v[168:171], v[82:97]
	s_waitcnt lgkmcnt(1)
	v_mfma_f32_32x32x16_bf16 v[50:65], v[180:183], v[164:167], v[50:65]
	s_waitcnt lgkmcnt(0)
	v_mfma_f32_32x32x16_bf16 v[50:65], v[184:187], v[168:171], v[50:65]
	s_waitcnt vmcnt(2)
	ds_write_b128 v141, v[148:151] offset:32768
	ds_write_b128 v141, v[152:155] offset:40960
	ds_write_b128 v141, v[156:159] offset:49152
	ds_write_b128 v141, v[160:163] offset:57344
	s_waitcnt lgkmcnt(0)
	s_barrier
; #define R2_LOADS(src, rstride, sl) do { _Pragma("unroll") for (int i = 0; i < 4; ++i) sr[i] = *(const v4u*)((src) + (size_t)(srow + 128 * i) * (rstride) + 32 * (sl) + 8 * sc4); } while (0)
; #define R2_STORES(bf) do { _Pragma("unroll") for (int i = 0; i < 4; ++i) *(LAS v4u*)(lds + (bf) * R2_SBUF + sso + 128 * i * 64) = sr[i]; } while (0)
;     ...
;           for (int sl = 0; sl < 8; ++sl) {
;               if (sl + 1 < 8) R2_LOADS(src, 256, sl + 1);
;               const bf16x8_t bq0 = *(const bf16x8_t*)(qg + 32 * sl), bq1 = *(const bf16x8_t*)(qg + 32 * sl + 16);
;               R2_SLICE(sl & 1, bq0, bq1);
;               if (sl + 1 < 8) R2_STORES((sl + 1) & 1);
;               __syncthreads();
;           } }
	global_load_dwordx4 v[148:151], v[130:131], off offset:256
	global_load_dwordx4 v[152:155], v[132:133], off offset:256
	global_load_dwordx4 v[156:159], v[134:135], off offset:256
	global_load_dwordx4 v[160:163], v[136:137], off offset:256
	s_waitcnt vmcnt(22)
	v_and_b32_e32 v164, 63, v228
	v_lshl_add_u32 v164, v164, 4, s70
	ds_read_b128 v[164:167], v164 offset:6144
	v_and_b32_e32 v168, 63, v228
	v_lshl_add_u32 v168, v168, 4, s70
	ds_read_b128 v[168:171], v168 offset:7168
	ds_read_b128 v[172:175], v218
	ds_read_b128 v[176:179], v219
	ds_read_b128 v[180:183], v220
	ds_read_b128 v[184:187], v221
	ds_read_b128 v[188:191], v222
	ds_read_b128 v[204:207], v223
	s_waitcnt lgkmcnt(5)
	v_mfma_f32_32x32x16_bf16 v[0:15], v[172:175], v[164:167], v[0:15]
	s_waitcnt lgkmcnt(4)
	v_mfma_f32_32x32x16_bf16 v[0:15], v[176:179], v[168:171], v[0:15]
	s_add_i32 m0, s70, 0x1640
	s_nop 0
	global_load_lds_dwordx4 v[138:139], off offset:448
	s_add_i32 m0, s70, 0x1a20
	s_nop 0
	global_load_lds_dwordx4 v[138:139], off offset:480
	ds_read_b128 v[172:175], v224
	ds_read_b128 v[176:179], v225
	s_waitcnt lgkmcnt(5)
	v_mfma_f32_32x32x16_bf16 v[16:31], v[180:183], v[164:167], v[16:31]
	s_waitcnt lgkmcnt(4)
	v_mfma_f32_32x32x16_bf16 v[16:31], v[184:187], v[168:171], v[16:31]
	ds_read_b128 v[180:183], v226
	ds_read_b128 v[184:187], v227
	s_waitcnt lgkmcnt(5)
	v_mfma_f32_32x32x16_bf16 v[34:49], v[188:191], v[164:167], v[34:49]
	s_waitcnt lgkmcnt(4)
	v_mfma_f32_32x32x16_bf16 v[34:49], v[204:207], v[168:171], v[34:49]
	ds_read_b128 v[188:191], v237
	ds_read_b128 v[204:207], v238
	s_waitcnt lgkmcnt(5)
	v_mfma_f32_32x32x16_bf16 v[66:81], v[172:175], v[164:167], v[66:81]
	s_waitcnt lgkmcnt(4)
	v_mfma_f32_32x32x16_bf16 v[66:81], v[176:179], v[168:171], v[66:81]
	ds_read_b128 v[172:175], v239
	ds_read_b128 v[176:179], v240
	s_waitcnt lgkmcnt(5)
	v_mfma_f32_32x32x16_bf16 v[98:113], v[180:183], v[164:167], v[98:113]
	s_waitcnt lgkmcnt(4)
	v_mfma_f32_32x32x16_bf16 v[98:113], v[184:187], v[168:171], v[98:113]
	ds_read_b128 v[180:183], v192
	ds_read_b128 v[184:187], v193
	s_waitcnt lgkmcnt(5)
	v_mfma_f32_32x32x16_bf16 v[114:129], v[188:191], v[164:167], v[114:129]
	s_waitcnt lgkmcnt(4)
	v_mfma_f32_32x32x16_bf16 v[114:129], v[204:207], v[168:171], v[114:129]
	s_waitcnt lgkmcnt(3)
	v_mfma_f32_32x32x16_bf16 v[82:97], v[172:175], v[164:167], v[82:97]
	s_waitcnt lgkmcnt(2)
	v_mfma_f32_32x32x16_bf16 v[82:97], v[176:179], v[168:171], v[82:97]
	s_waitcnt lgkmcnt(1)
	v_mfma_f32_32x32x16_bf16 v[50:65], v[180:183], v[164:167], v[50:65]
	s_waitcnt lgkmcnt(0)
	v_mfma_f32_32x32x16_bf16 v[50:65], v[184:187], v[168:171], v[50:65]
	s_waitcnt vmcnt(2)
	ds_write_b128 v141, v[148:151]
	ds_write_b128 v141, v[152:155] offset:8192
	ds_write_b128 v141, v[156:159] offset:16384
	ds_write_b128 v141, v[160:163] offset:24576
	s_waitcnt lgkmcnt(0)
	s_barrier
	global_load_dwordx4 v[148:151], v[130:131], off offset:320
	global_load_dwordx4 v[152:155], v[132:133], off offset:320
	global_load_dwordx4 v[156:159], v[134:135], off offset:320
	global_load_dwordx4 v[160:163], v[136:137], off offset:320
	s_waitcnt vmcnt(22)
	v_and_b32_e32 v164, 63, v228
	v_lshl_add_u32 v164, v164, 4, s70
	ds_read_b128 v[164:167], v164
	v_and_b32_e32 v168, 63, v228
	v_lshl_add_u32 v168, v168, 4, s70
	ds_read_b128 v[168:171], v168 offset:1024
	ds_read_b128 v[172:175], v142
	ds_read_b128 v[176:179], v143
	ds_read_b128 v[180:183], v144
	ds_read_b128 v[184:187], v145
	ds_read_b128 v[188:191], v146
	ds_read_b128 v[204:207], v195
	s_waitcnt lgkmcnt(5)
	v_mfma_f32_32x32x16_bf16 v[0:15], v[172:175], v[164:167], v[0:15]
	s_waitcnt lgkmcnt(4)
	v_mfma_f32_32x32x16_bf16 v[0:15], v[176:179], v[168:171], v[0:15]
	ds_read_b128 v[172:175], v208
	ds_read_b128 v[176:179], v209
	s_waitcnt lgkmcnt(5)
	v_mfma_f32_32x32x16_bf16 v[16:31], v[180:183], v[164:167], v[16:31]
	s_waitcnt lgkmcnt(4)
	v_mfma_f32_32x32x16_bf16 v[16:31], v[184:187], v[168:171], v[16:31]
	ds_read_b128 v[180:183], v210
	ds_read_b128 v[184:187], v211
	s_waitcnt lgkmcnt(5)
	v_mfma_f32_32x32x16_bf16 v[34:49], v[188:191], v[164:167], v[34:49]
	s_waitcnt lgkmcnt(4)
	v_mfma_f32_32x32x16_bf16 v[34:49], v[204:207], v[168:171], v[34:49]
	ds_read_b128 v[188:191], v212
	ds_read_b128 v[204:207], v213
	s_waitcnt lgkmcnt(5)
	v_mfma_f32_32x32x16_bf16 v[66:81], v[172:175], v[164:167], v[66:81]
	s_waitcnt lgkmcnt(4)
	v_mfma_f32_32x32x16_bf16 v[66:81], v[176:179], v[168:171], v[66:81]
	ds_read_b128 v[172:175], v214
	ds_read_b128 v[176:179], v215
	s_waitcnt lgkmcnt(5)
	v_mfma_f32_32x32x16_bf16 v[98:113], v[180:183], v[164:167], v[98:113]
	s_waitcnt lgkmcnt(4)
	v_mfma_f32_32x32x16_bf16 v[98:113], v[184:187], v[168:171], v[98:113]
	ds_read_b128 v[180:183], v216
	ds_read_b128 v[184:187], v217
	s_waitcnt lgkmcnt(5)
	v_mfma_f32_32x32x16_bf16 v[114:129], v[188:191], v[164:167], v[114:129]
	s_waitcnt lgkmcnt(4)
	v_mfma_f32_32x32x16_bf16 v[114:129], v[204:207], v[168:171], v[114:129]
	s_waitcnt lgkmcnt(3)
	v_mfma_f32_32x32x16_bf16 v[82:97], v[172:175], v[164:167], v[82:97]
	s_waitcnt lgkmcnt(2)
	v_mfma_f32_32x32x16_bf16 v[82:97], v[176:179], v[168:171], v[82:97]
	s_waitcnt lgkmcnt(1)
	v_mfma_f32_32x32x16_bf16 v[50:65], v[180:183], v[164:167], v[50:65]
	s_waitcnt lgkmcnt(0)
	v_mfma_f32_32x32x16_bf16 v[50:65], v[184:187], v[168:171], v[50:65]
	s_waitcnt vmcnt(0)
	ds_write_b128 v141, v[148:151] offset:32768
	ds_write_b128 v141, v[152:155] offset:40960
	ds_write_b128 v141, v[156:159] offset:49152
	ds_write_b128 v141, v[160:163] offset:57344
	s_waitcnt lgkmcnt(0)
	s_barrier
; #define R2_LOADS(src, rstride, sl) do { _Pragma("unroll") for (int i = 0; i < 4; ++i) sr[i] = *(const v4u*)((src) + (size_t)(srow + 128 * i) * (rstride) + 32 * (sl) + 8 * sc4); } while (0)
; #define R2_STORES(bf) do { _Pragma("unroll") for (int i = 0; i < 4; ++i) *(LAS v4u*)(lds + (bf) * R2_SBUF + sso + 128 * i * 64) = sr[i]; } while (0)
;     ...
;           for (int sl = 0; sl < 8; ++sl) {
;               if (sl + 1 < 8) R2_LOADS(src, 256, sl + 1);
;               const bf16x8_t bq0 = *(const bf16x8_t*)(qg + 32 * sl), bq1 = *(const bf16x8_t*)(qg + 32 * sl + 16);
;               R2_SLICE(sl & 1, bq0, bq1);
;               if (sl + 1 < 8) R2_STORES((sl + 1) & 1);
;               __syncthreads();
;           } }
	global_load_dwordx4 v[148:151], v[130:131], off offset:384
	global_load_dwordx4 v[152:155], v[132:133], off offset:384
	global_load_dwordx4 v[156:159], v[134:135], off offset:384
	global_load_dwordx4 v[160:163], v[136:137], off offset:384
	s_waitcnt vmcnt(20)
	v_and_b32_e32 v164, 63, v228
	v_lshl_add_u32 v164, v164, 4, s70
	ds_read_b128 v[164:167], v164 offset:2048
	v_and_b32_e32 v168, 63, v228
	v_lshl_add_u32 v168, v168, 4, s70
	ds_read_b128 v[168:171], v168 offset:3072
	ds_read_b128 v[172:175], v218
	ds_read_b128 v[176:179], v219
	ds_read_b128 v[180:183], v220
	ds_read_b128 v[184:187], v221
	ds_read_b128 v[188:191], v222
	ds_read_b128 v[204:207], v223
	s_waitcnt lgkmcnt(5)
	v_mfma_f32_32x32x16_bf16 v[0:15], v[172:175], v[164:167], v[0:15]
	s_waitcnt lgkmcnt(4)
	v_mfma_f32_32x32x16_bf16 v[0:15], v[176:179], v[168:171], v[0:15]
	ds_read_b128 v[172:175], v224
	ds_read_b128 v[176:179], v225
	s_waitcnt lgkmcnt(5)
	v_mfma_f32_32x32x16_bf16 v[16:31], v[180:183], v[164:167], v[16:31]
	s_waitcnt lgkmcnt(4)
	v_mfma_f32_32x32x16_bf16 v[16:31], v[184:187], v[168:171], v[16:31]
	ds_read_b128 v[180:183], v226
	ds_read_b128 v[184:187], v227
	s_waitcnt lgkmcnt(5)
	v_mfma_f32_32x32x16_bf16 v[34:49], v[188:191], v[164:167], v[34:49]
	s_waitcnt lgkmcnt(4)
	v_mfma_f32_32x32x16_bf16 v[34:49], v[204:207], v[168:171], v[34:49]
	ds_read_b128 v[188:191], v237
	ds_read_b128 v[204:207], v238
	s_waitcnt lgkmcnt(5)
	v_mfma_f32_32x32x16_bf16 v[66:81], v[172:175], v[164:167], v[66:81]
	s_waitcnt lgkmcnt(4)
	v_mfma_f32_32x32x16_bf16 v[66:81], v[176:179], v[168:171], v[66:81]
	ds_read_b128 v[172:175], v239
	ds_read_b128 v[176:179], v240
	s_waitcnt lgkmcnt(5)
	v_mfma_f32_32x32x16_bf16 v[98:113], v[180:183], v[164:167], v[98:113]
	s_waitcnt lgkmcnt(4)
	v_mfma_f32_32x32x16_bf16 v[98:113], v[184:187], v[168:171], v[98:113]
	ds_read_b128 v[180:183], v192
	ds_read_b128 v[184:187], v193
	s_waitcnt lgkmcnt(5)
	v_mfma_f32_32x32x16_bf16 v[114:129], v[188:191], v[164:167], v[114:129]
	s_waitcnt lgkmcnt(4)
	v_mfma_f32_32x32x16_bf16 v[114:129], v[204:207], v[168:171], v[114:129]
	s_waitcnt lgkmcnt(3)
	v_mfma_f32_32x32x16_bf16 v[82:97], v[172:175], v[164:167], v[82:97]
	s_waitcnt lgkmcnt(2)
	v_mfma_f32_32x32x16_bf16 v[82:97], v[176:179], v[168:171], v[82:97]
	s_waitcnt lgkmcnt(1)
	v_mfma_f32_32x32x16_bf16 v[50:65], v[180:183], v[164:167], v[50:65]
	s_waitcnt lgkmcnt(0)
	v_mfma_f32_32x32x16_bf16 v[50:65], v[184:187], v[168:171], v[50:65]
	s_waitcnt vmcnt(0)
	ds_write_b128 v141, v[148:151]
	ds_write_b128 v141, v[152:155] offset:8192
	ds_write_b128 v141, v[156:159] offset:16384
	ds_write_b128 v141, v[160:163] offset:24576
	s_waitcnt lgkmcnt(0)
	s_barrier
	global_load_dwordx4 v[148:151], v[130:131], off offset:448
	s_nop 0
	global_load_dwordx4 v[130:133], v[132:133], off offset:448
	s_nop 0
	global_load_dwordx4 v[152:155], v[134:135], off offset:448
	s_nop 0
	global_load_dwordx4 v[134:137], v[136:137], off offset:448
	s_nop 0
	s_waitcnt vmcnt(18)
	v_and_b32_e32 v156, 63, v228
	v_lshl_add_u32 v156, v156, 4, s70
	ds_read_b128 v[156:159], v156 offset:4096
	v_and_b32_e32 v160, 63, v228
	v_lshl_add_u32 v160, v160, 4, s70
	ds_read_b128 v[160:163], v160 offset:5120
	ds_read_b128 v[164:167], v142
	ds_read_b128 v[168:171], v143
	ds_read_b128 v[172:175], v144
	ds_read_b128 v[142:145], v145
	ds_read_b128 v[176:179], v146
	ds_read_b128 v[180:183], v195
	s_waitcnt lgkmcnt(5)
	v_mfma_f32_32x32x16_bf16 v[0:15], v[164:167], v[156:159], v[0:15]
	s_waitcnt lgkmcnt(4)
	v_mfma_f32_32x32x16_bf16 v[0:15], v[168:171], v[160:163], v[0:15]
	ds_read_b128 v[164:167], v208
	ds_read_b128 v[168:171], v209
	s_waitcnt lgkmcnt(5)
	v_mfma_f32_32x32x16_bf16 v[16:31], v[172:175], v[156:159], v[16:31]
	s_waitcnt lgkmcnt(4)
	v_mfma_f32_32x32x16_bf16 v[16:31], v[142:145], v[160:163], v[16:31]
	ds_read_b128 v[142:145], v210
	ds_read_b128 v[172:175], v211
	s_waitcnt lgkmcnt(5)
	v_mfma_f32_32x32x16_bf16 v[34:49], v[176:179], v[156:159], v[34:49]
	s_waitcnt lgkmcnt(4)
	v_mfma_f32_32x32x16_bf16 v[34:49], v[180:183], v[160:163], v[34:49]
	ds_read_b128 v[176:179], v212
	ds_read_b128 v[180:183], v213
	s_waitcnt lgkmcnt(5)
	v_mfma_f32_32x32x16_bf16 v[66:81], v[164:167], v[156:159], v[66:81]
	s_waitcnt lgkmcnt(4)
	v_mfma_f32_32x32x16_bf16 v[66:81], v[168:171], v[160:163], v[66:81]
	ds_read_b128 v[164:167], v214
	ds_read_b128 v[168:171], v215
	s_waitcnt lgkmcnt(5)
	v_mfma_f32_32x32x16_bf16 v[98:113], v[142:145], v[156:159], v[98:113]
	s_waitcnt lgkmcnt(4)
	v_mfma_f32_32x32x16_bf16 v[98:113], v[172:175], v[160:163], v[98:113]
	ds_read_b128 v[142:145], v216
	ds_read_b128 v[172:175], v217
	s_waitcnt lgkmcnt(5)
	v_mfma_f32_32x32x16_bf16 v[114:129], v[176:179], v[156:159], v[114:129]
	s_waitcnt lgkmcnt(4)
	v_mfma_f32_32x32x16_bf16 v[114:129], v[180:183], v[160:163], v[114:129]
	s_waitcnt lgkmcnt(3)
	v_mfma_f32_32x32x16_bf16 v[82:97], v[164:167], v[156:159], v[82:97]
	s_waitcnt lgkmcnt(2)
	v_mfma_f32_32x32x16_bf16 v[82:97], v[168:171], v[160:163], v[82:97]
	s_waitcnt lgkmcnt(1)
	v_mfma_f32_32x32x16_bf16 v[50:65], v[142:145], v[156:159], v[50:65]
	s_waitcnt lgkmcnt(0)
	v_mfma_f32_32x32x16_bf16 v[50:65], v[172:175], v[160:163], v[50:65]
	s_waitcnt vmcnt(0)
	ds_write_b128 v141, v[148:151] offset:32768
	ds_write_b128 v141, v[130:133] offset:40960
	ds_write_b128 v141, v[152:155] offset:49152
	ds_write_b128 v141, v[134:137] offset:57344
	s_waitcnt lgkmcnt(0)
	s_barrier
; #define LAS __attribute__((address_space(3)))
; #define R2_LOADS(src, rstride, sl) do { _Pragma("unroll") for (int i = 0; i < 4; ++i) sr[i] = *(const v4u*)((src) + (size_t)(srow + 128 * i) * (rstride) + 32 * (sl) + 8 * sc4); } while (0)
; #define R2_STORES(bf) do { _Pragma("unroll") for (int i = 0; i < 4; ++i) *(LAS v4u*)(lds + (bf) * R2_SBUF + sso + 128 * i * 64) = sr[i]; } while (0)
;     ...
;           for (int sl = 0; sl < 8; ++sl) {
;               if (sl + 1 < 8) R2_LOADS(src, 256, sl + 1);
;               const bf16x8_t bq0 = *(const bf16x8_t*)(qg + 32 * sl), bq1 = *(const bf16x8_t*)(qg + 32 * sl + 16);
;               R2_SLICE(sl & 1, bq0, bq1);
;               if (sl + 1 < 8) R2_STORES((sl + 1) & 1);
;               __syncthreads();
;           } }
;         { R2_IDS const float qdec = __builtin_amdgcn_exp2f((float)(32 * nt + r + 1 + odd * 128) * lg2);
; #pragma unroll
;           for (int et = 0; et < 8; ++et)
; #pragma unroll
;               for (int i = 0; i < 16; ++i) acc[et][i] *= qdec; }
;         const int nmt = odd ? 4 + nt + 1 : nt + 1;
;         if (!(dry && (R2_SKIP & 2))) { R2_IDS
; #pragma unroll
;             for (int i = 0; i < 8; ++i) { const int ch = t_ + NTHR * i, n = ch >> 5, cc = ch & 31;
;                 *(LAS v4u*)(lds + R2_SOFF + n * 512 + ((cc ^ (n & 31)) * 16)) = *(const v4u*)(Q + ((size_t)(bh * SEQ + tq0 + n)) * 256 + cc * 8); }
;             __syncthreads();
	s_waitcnt vmcnt(12)
	v_and_b32_e32 v130, 63, v228
	v_lshl_add_u32 v130, v130, 4, s70
	ds_read_b128 v[130:133], v130 offset:6144
	v_and_b32_e32 v134, 63, v228
	v_lshl_add_u32 v134, v134, 4, s70
	ds_read_b128 v[134:137], v134 offset:7168
	ds_read_b128 v[142:145], v218
	ds_read_b128 v[146:149], v219
	ds_read_b128 v[150:153], v220
	ds_read_b128 v[154:157], v221
	ds_read_b128 v[158:161], v222
	ds_read_b128 v[162:165], v223
	s_waitcnt lgkmcnt(5)
	v_mfma_f32_32x32x16_bf16 v[0:15], v[142:145], v[130:133], v[0:15]
	s_waitcnt lgkmcnt(4)
	v_mfma_f32_32x32x16_bf16 v[0:15], v[146:149], v[134:137], v[0:15]
	ds_read_b128 v[142:145], v224
	ds_read_b128 v[146:149], v225
	s_waitcnt lgkmcnt(5)
	v_mfma_f32_32x32x16_bf16 v[16:31], v[150:153], v[130:133], v[16:31]
	s_waitcnt lgkmcnt(4)
	v_mfma_f32_32x32x16_bf16 v[16:31], v[154:157], v[134:137], v[16:31]
	ds_read_b128 v[150:153], v226
	ds_read_b128 v[154:157], v227
	s_waitcnt lgkmcnt(5)
	v_mfma_f32_32x32x16_bf16 v[34:49], v[158:161], v[130:133], v[34:49]
	s_waitcnt lgkmcnt(4)
	v_mfma_f32_32x32x16_bf16 v[34:49], v[162:165], v[134:137], v[34:49]
	ds_read_b128 v[158:161], v237
	ds_read_b128 v[162:165], v238
	s_waitcnt lgkmcnt(5)
	v_mfma_f32_32x32x16_bf16 v[66:81], v[142:145], v[130:133], v[66:81]
	s_waitcnt lgkmcnt(4)
	v_mfma_f32_32x32x16_bf16 v[66:81], v[146:149], v[134:137], v[66:81]
	ds_read_b128 v[142:145], v239
	ds_read_b128 v[146:149], v240
	s_waitcnt lgkmcnt(5)
	v_mfma_f32_32x32x16_bf16 v[98:113], v[150:153], v[130:133], v[98:113]
	s_waitcnt lgkmcnt(4)
	v_mfma_f32_32x32x16_bf16 v[98:113], v[154:157], v[134:137], v[98:113]
	ds_read_b128 v[150:153], v192
	ds_read_b128 v[154:157], v193
	s_waitcnt lgkmcnt(5)
	v_mfma_f32_32x32x16_bf16 v[114:129], v[158:161], v[130:133], v[114:129]
	s_waitcnt lgkmcnt(4)
	v_mfma_f32_32x32x16_bf16 v[114:129], v[162:165], v[134:137], v[114:129]
	s_waitcnt lgkmcnt(3)
	v_mfma_f32_32x32x16_bf16 v[82:97], v[142:145], v[130:133], v[82:97]
	s_waitcnt lgkmcnt(2)
	v_mfma_f32_32x32x16_bf16 v[82:97], v[146:149], v[134:137], v[82:97]
	s_waitcnt lgkmcnt(1)
	v_mfma_f32_32x32x16_bf16 v[50:65], v[150:153], v[130:133], v[50:65]
	s_waitcnt lgkmcnt(0)
	v_mfma_f32_32x32x16_bf16 v[50:65], v[154:157], v[134:137], v[50:65]
	v_mov_b32_e32 v148, v33
	v_mov_b32_e32 v130, v33
	s_barrier
	v_mov_b32_e32 v133, v32
	v_lshlrev_b32_e32 v131, 4, v130
	v_add_u32_e32 v134, 0x200, v130
	v_and_b32_e32 v132, 0x1f0, v131
	v_ashrrev_i32_e32 v131, 5, v130
	v_ashrrev_i32_e32 v141, 5, v134
	v_lshl_add_u64 v[146:147], s[24:25], 0, v[132:133]
	v_add_u32_e32 v132, s19, v131
	v_add_u32_e32 v134, s19, v141
	v_ashrrev_i32_e32 v133, 31, v132
	v_ashrrev_i32_e32 v135, 31, v134
	v_lshlrev_b64 v[132:133], 9, v[132:133]
	v_lshlrev_b64 v[134:135], 9, v[134:135]
	v_lshl_add_u64 v[132:133], v[146:147], 0, v[132:133]
	v_lshl_add_u64 v[136:137], v[146:147], 0, v[134:135]
	v_add_u32_e32 v142, 0x400, v130
	global_load_dwordx4 v[132:135], v[132:133], off
	s_nop 0
	global_load_dwordx4 v[136:139], v[136:137], off
	v_ashrrev_i32_e32 v170, 5, v142
	v_add_u32_e32 v142, s19, v170
	v_ashrrev_i32_e32 v143, 31, v142
	v_add_u32_e32 v149, 0x600, v130
	v_lshlrev_b64 v[142:143], 9, v[142:143]
	v_ashrrev_i32_e32 v171, 5, v149
	v_lshl_add_u64 v[142:143], v[146:147], 0, v[142:143]
	v_add_u32_e32 v150, s19, v171
	global_load_dwordx4 v[142:145], v[142:143], off
	v_ashrrev_i32_e32 v151, 31, v150
	v_add_u32_e32 v149, 0x800, v130
	v_lshlrev_b64 v[150:151], 9, v[150:151]
	v_ashrrev_i32_e32 v172, 5, v149
	v_lshl_add_u64 v[150:151], v[146:147], 0, v[150:151]
	v_add_u32_e32 v154, s19, v172
	global_load_dwordx4 v[150:153], v[150:151], off
	v_ashrrev_i32_e32 v155, 31, v154
	v_add_u32_e32 v149, 0xa00, v130
	v_lshlrev_b64 v[154:155], 9, v[154:155]
	v_ashrrev_i32_e32 v173, 5, v149
	v_lshl_add_u64 v[154:155], v[146:147], 0, v[154:155]
	v_add_u32_e32 v158, s19, v173
	global_load_dwordx4 v[154:157], v[154:155], off
	v_ashrrev_i32_e32 v159, 31, v158
	v_add_u32_e32 v149, 0xc00, v130
	v_lshlrev_b64 v[158:159], 9, v[158:159]
	v_ashrrev_i32_e32 v174, 5, v149
	v_lshl_add_u64 v[158:159], v[146:147], 0, v[158:159]
	v_add_u32_e32 v162, s19, v174
	v_add_u32_e32 v149, 0xe00, v130
	global_load_dwordx4 v[158:161], v[158:159], off
	v_ashrrev_i32_e32 v163, 31, v162
	v_ashrrev_i32_e32 v175, 5, v149
	v_lshlrev_b64 v[162:163], 9, v[162:163]
	v_add_u32_e32 v166, s19, v175
	v_lshl_add_u64 v[162:163], v[146:147], 0, v[162:163]
	v_ashrrev_i32_e32 v167, 31, v166
	global_load_dwordx4 v[162:165], v[162:163], off
	v_lshlrev_b64 v[166:167], 9, v[166:167]
	v_lshl_add_u64 v[146:147], v[146:147], 0, v[166:167]
	global_load_dwordx4 v[166:169], v[146:147], off
	v_lshlrev_b32_e32 v147, 9, v131
	v_xor_b32_e32 v131, v131, v130
	v_lshlrev_b32_e32 v131, 4, v131
	v_lshlrev_b32_e32 v149, 9, v141
	v_xor_b32_e32 v141, v141, v130
	v_and_b32_e32 v131, 0x1f0, v131
	v_lshlrev_b32_e32 v141, 4, v141
	v_add3_u32 v131, s93, v147, v131
	v_and_b32_e32 v141, 0x1f0, v141
	v_add3_u32 v141, s93, v149, v141
	s_mov_b32 s19, 0x800000
	v_cmp_gt_f32_e32 vcc, s19, v140
	s_and_b64 s[34:35], vcc, exec
	s_cselect_b32 s19, 32, 0
	s_cmp_eq_u32 s40, 0
	v_ldexp_f32 v140, v140, s19
	s_cselect_b64 s[34:35], -1, 0
	v_log_f32_e32 v140, v140
	s_and_b64 s[52:53], s[34:35], exec
	s_cselect_b32 s19, 1, 5
	v_cndmask_b32_e32 v146, 0, v236, vcc
	s_add_i32 s19, s19, s45
	s_waitcnt vmcnt(7)
	ds_write_b128 v131, v[132:135]
	s_waitcnt vmcnt(6)
	ds_write_b128 v141, v[136:139]
	v_xor_b32_e32 v132, v170, v130
	v_lshlrev_b32_e32 v132, 4, v132
	v_lshlrev_b32_e32 v131, 9, v170
	v_and_b32_e32 v132, 0x1f0, v132
	v_add3_u32 v131, s93, v131, v132
	v_xor_b32_e32 v132, v171, v130
	v_lshlrev_b32_e32 v132, 4, v132
	v_and_b32_e32 v132, 0x1f0, v132
	s_waitcnt vmcnt(5)
	ds_write_b128 v131, v[142:145]
	v_lshlrev_b32_e32 v131, 9, v171
	v_add3_u32 v131, s93, v131, v132
	v_xor_b32_e32 v132, v172, v130
	v_lshlrev_b32_e32 v132, 4, v132
	v_and_b32_e32 v132, 0x1f0, v132
	v_sub_f32_e32 v149, v140, v146
	s_waitcnt vmcnt(4)
	ds_write_b128 v131, v[150:153]
	v_lshlrev_b32_e32 v131, 9, v172
	v_add3_u32 v131, s93, v131, v132
	v_xor_b32_e32 v132, v173, v130
	v_lshlrev_b32_e32 v132, 4, v132
	v_and_b32_e32 v132, 0x1f0, v132
	s_cmp_ge_i32 s46, s19
	s_waitcnt vmcnt(3)
	ds_write_b128 v131, v[154:157]
	v_lshlrev_b32_e32 v131, 9, v173
	v_add3_u32 v131, s93, v131, v132
	v_xor_b32_e32 v132, v174, v130
	v_lshlrev_b32_e32 v132, 4, v132
	v_and_b32_e32 v132, 0x1f0, v132
	s_waitcnt vmcnt(2)
	ds_write_b128 v131, v[158:161]
	v_lshlrev_b32_e32 v131, 9, v174
	v_add3_u32 v131, s93, v131, v132
	v_xor_b32_e32 v132, v175, v130
	v_lshlrev_b32_e32 v132, 4, v132
	v_and_b32_e32 v132, 0x1f0, v132
	s_waitcnt vmcnt(1)
	ds_write_b128 v131, v[162:165]
	v_lshlrev_b32_e32 v131, 9, v175
	v_add3_u32 v131, s93, v131, v132
	s_waitcnt vmcnt(0)
	ds_write_b128 v131, v[166:169]
	s_waitcnt lgkmcnt(0)
	s_barrier
; #define LAS __attribute__((address_space(3)))
; #define MFMA32(a, b, c) __builtin_amdgcn_mfma_f32_32x32x16_bf16((a), (b), (c), 0, 0, 0)
; __device__ __forceinline__ unsigned cvtpk(float lo, float hi) { return pg8::cvt_pk_bf16(lo, hi); }
;     ...
;             const LAS unsigned char* qrow = lds + R2_SOFF + (32 * nt + r) * 512;
;             for (int mt = eh; mt < nmt; mt += 2) {
;                 f32x16 p;
; #pragma unroll
;                 for (int i = 0; i < 16; ++i) p[i] = 0.f;
;                 const bf16* kb = K + ((size_t)(bh * SEQ + tk0 + 32 * mt + r)) * 256 + 8 * hh;
; #pragma unroll
;                 for (int kh = 0; kh < 2; ++kh) { bf16x8_t kf[8];
; #pragma unroll
;                     for (int jj = 0; jj < 8; ++jj) kf[jj] = *(const bf16x8_t*)(kb + (8 * kh + jj) * 16);
; #pragma unroll
;                     for (int jj = 0; jj < 8; ++jj) p = MFMA32(kf[jj], *(const LAS bf16x8_t*)(qrow + (((2 * (8 * kh + jj) + hh) ^ r) * 16)), p); }
;                 const int nq = tq0 + 32 * nt + r, mk = tk0 + 32 * mt + 4 * hh;
; #pragma unroll
;                 for (int i4 = 0; i4 < 4; ++i4) { float v[4];
; #pragma unroll
;                     for (int k = 0; k < 4; ++k) { const int dist = nq - (mk + 8 * i4 + k); v[k] = dist < 0 ? 0.f : p[4 * i4 + k] * __builtin_amdgcn_exp2f((float)dist * lg2); }
;                     v2u wv; wv.x = cvtpk(v[0], v[1]); wv.y = cvtpk(v[2], v[3]);
;                     *(LAS v2u*)(lds + ((32 * nt + r) * R2_STR + 32 * mt + 8 * i4 + 4 * hh) * 2) = wv; }
	s_cbranch_scc1 .LBB0_721
	v_and_b32_e32 v150, 31, v130
	v_bfe_u32 v135, v130, 5, 1
	v_or_b32_e32 v132, s47, v150
	v_lshrrev_b32_e32 v134, 5, v130
	v_lshlrev_b32_e32 v130, 4, v135
	v_mov_b32_e32 v131, v32
	v_bitop3_b32 v151, v135, v150, 24 bitop3:0x36
	v_lshl_add_u64 v[146:147], s[26:27], 0, v[130:131]
	v_lshlrev_b32_e32 v130, 2, v135
	v_mul_u32_u24_e32 v131, 0x108, v132
	v_lshlrev_b32_e32 v166, 4, v151
	v_bitop3_b32 v151, v135, v150, 26 bitop3:0x36
	v_lshl_add_u32 v133, v132, 9, s93
	v_bitop3_b32 v132, v134, v150, 1 bitop3:0x6c
	v_bitop3_b32 v134, v135, v150, 2 bitop3:0x36
	v_bitop3_b32 v136, v135, v150, 4 bitop3:0x36
	v_bitop3_b32 v137, v135, v150, 6 bitop3:0x36
	v_bitop3_b32 v138, v135, v150, 8 bitop3:0x36
	v_bitop3_b32 v139, v135, v150, 10 bitop3:0x36
	v_bitop3_b32 v140, v135, v150, 12 bitop3:0x36
	v_bitop3_b32 v141, v135, v150, 14 bitop3:0x36
	v_bitop3_b32 v142, v135, v150, 16 bitop3:0x36
	v_bitop3_b32 v143, v135, v150, 18 bitop3:0x36
	v_bitop3_b32 v144, v135, v150, 20 bitop3:0x36
	v_bitop3_b32 v145, v135, v150, 22 bitop3:0x36
	v_lshlrev_b32_e32 v167, 4, v151
	v_bitop3_b32 v151, v135, v150, 28 bitop3:0x36
	v_bitop3_b32 v135, v135, v150, 30 bitop3:0x36
	v_add3_u32 v131, s91, v131, v130
	s_add_i32 s49, s18, s5
	s_add_i32 s52, s91, s6
	v_lshlrev_b32_e32 v132, 4, v132
	v_lshlrev_b32_e32 v134, 4, v134
	v_lshlrev_b32_e32 v136, 4, v136
	v_lshlrev_b32_e32 v137, 4, v137
	v_lshlrev_b32_e32 v138, 4, v138
	v_lshlrev_b32_e32 v139, 4, v139
	v_lshlrev_b32_e32 v140, 4, v140
	v_lshlrev_b32_e32 v141, 4, v141
	v_lshlrev_b32_e32 v142, 4, v142
	v_lshlrev_b32_e32 v143, 4, v143
	v_lshlrev_b32_e32 v144, 4, v144
	v_lshlrev_b32_e32 v145, 4, v145
	v_lshlrev_b32_e32 v168, 4, v151
	v_lshlrev_b32_e32 v135, 4, v135
	v_lshl_add_u32 v151, v131, 1, 0
	v_sub_u32_e32 v131, s49, v130
	s_add_i32 s49, s47, s5
	v_add_u32_e32 v130, s52, v130
	v_subrev_u32_e32 v152, s6, v131
	v_sub_u32_e32 v153, s49, v130
	s_add_i32 s41, s52, s41
	v_add_u32_e32 v154, v133, v132
	v_add_u32_e32 v155, v133, v134
	v_add_u32_e32 v156, v133, v136
	v_add_u32_e32 v157, v133, v137
	v_add_u32_e32 v158, v133, v138
	v_add_u32_e32 v159, v133, v139
	v_add_u32_e32 v160, v133, v140
	v_add_u32_e32 v161, v133, v141
	v_add_u32_e32 v162, v133, v142
	v_add_u32_e32 v163, v133, v143
	v_add_u32_e32 v164, v133, v144
	v_add_u32_e32 v165, v133, v145
	v_add_u32_e32 v166, v133, v166
	v_add_u32_e32 v167, v133, v167
	v_add_u32_e32 v168, v133, v168
	v_add_u32_e32 v169, v133, v135
	s_mov_b32 s49, s46
